# S5 pass 1: next chunk's projection MFMAs issued inside the recurrence steps (MFMA/VALU interleave)
# speedup vs baseline: 1.0072x; 1.0031x over previous
.LBB0_848:
	v_cndmask_b32_e64 v184, v80, 0, s[10:11]
	v_cndmask_b32_e64 v185, v81, 0, s[10:11]
	v_cndmask_b32_e64 v186, v82, 0, s[10:11]
	v_cndmask_b32_e64 v187, v83, 0, s[10:11]
	s_nop 1
	v_mfma_f32_16x16x32_bf16 v[188:191], v[184:187], v[0:3], 0
	v_mfma_f32_16x16x32_bf16 v[192:195], v[184:187], v[4:7], 0
	v_mfma_f32_16x16x32_bf16 v[196:199], v[184:187], v[8:11], 0
	v_mfma_f32_16x16x32_bf16 v[200:203], v[184:187], v[12:15], 0
	v_mfma_f32_16x16x32_bf16 v[204:207], v[184:187], v[16:19], 0
	v_mfma_f32_16x16x32_bf16 v[208:211], v[184:187], v[20:23], 0
	v_mfma_f32_16x16x32_bf16 v[212:215], v[184:187], v[24:27], 0
	v_mfma_f32_16x16x32_bf16 v[216:219], v[184:187], v[28:31], 0
	s_nop 7
	v_permlane16_swap_b32_e32 v188, v192
	v_permlane16_swap_b32_e32 v189, v193
	v_permlane16_swap_b32_e32 v190, v194
	v_permlane16_swap_b32_e32 v191, v195
	v_permlane16_swap_b32_e32 v196, v200
	v_permlane16_swap_b32_e32 v197, v201
	v_permlane16_swap_b32_e32 v198, v202
	v_permlane16_swap_b32_e32 v199, v203
	v_permlane16_swap_b32_e32 v204, v208
	v_permlane16_swap_b32_e32 v205, v209
	v_permlane16_swap_b32_e32 v206, v210
	v_permlane16_swap_b32_e32 v207, v211
	v_permlane16_swap_b32_e32 v212, v216
	v_permlane16_swap_b32_e32 v213, v217
	v_permlane16_swap_b32_e32 v214, v218
	v_permlane16_swap_b32_e32 v215, v219
	v_permlane32_swap_b32_e32 v188, v196
	v_permlane32_swap_b32_e32 v189, v197
	v_permlane32_swap_b32_e32 v190, v198
	v_permlane32_swap_b32_e32 v191, v199
	v_permlane32_swap_b32_e32 v192, v200
	v_permlane32_swap_b32_e32 v193, v201
	v_permlane32_swap_b32_e32 v194, v202
	v_permlane32_swap_b32_e32 v195, v203
	v_permlane32_swap_b32_e32 v204, v212
	v_permlane32_swap_b32_e32 v205, v213
	v_permlane32_swap_b32_e32 v206, v214
	v_permlane32_swap_b32_e32 v207, v215
	v_permlane32_swap_b32_e32 v208, v216
	v_permlane32_swap_b32_e32 v209, v217
	v_permlane32_swap_b32_e32 v210, v218
	v_permlane32_swap_b32_e32 v211, v219
	s_nop 1
	v_cndmask_b32_e64 v184, v76, 0, s[10:11]
	v_cndmask_b32_e64 v185, v77, 0, s[10:11]
	v_cndmask_b32_e64 v186, v78, 0, s[10:11]
	v_cndmask_b32_e64 v187, v79, 0, s[10:11]
	v_fma_f32 v220, -v132, v89, v188
	v_fma_f32 v221, v132, v88, v204
	v_fma_f32 v88, v128, v88, v220
	v_fma_f32 v89, v128, v89, v221
	v_fma_f32 v220, -v132, v89, v189
	v_fma_f32 v221, v132, v88, v205
	v_fma_f32 v88, v128, v88, v220
	v_fma_f32 v89, v128, v89, v221
	v_fma_f32 v220, -v132, v89, v190
	v_fma_f32 v221, v132, v88, v206
	v_fma_f32 v88, v128, v88, v220
	v_fma_f32 v89, v128, v89, v221
	v_fma_f32 v220, -v132, v89, v191
	v_fma_f32 v221, v132, v88, v207
	v_fma_f32 v88, v128, v88, v220
	v_fma_f32 v89, v128, v89, v221
	v_mfma_f32_16x16x32_bf16 v[188:191], v[184:187], v[0:3], 0
	v_mfma_f32_16x16x32_bf16 v[204:207], v[184:187], v[16:19], 0
	v_fma_f32 v220, -v132, v89, v192
	v_fma_f32 v221, v132, v88, v208
	v_fma_f32 v88, v128, v88, v220
	v_fma_f32 v89, v128, v89, v221
	v_fma_f32 v220, -v132, v89, v193
	v_fma_f32 v221, v132, v88, v209
	v_fma_f32 v88, v128, v88, v220
	v_fma_f32 v89, v128, v89, v221
	v_fma_f32 v220, -v132, v89, v194
	v_fma_f32 v221, v132, v88, v210
	v_fma_f32 v88, v128, v88, v220
	v_fma_f32 v89, v128, v89, v221
	v_fma_f32 v220, -v132, v89, v195
	v_fma_f32 v221, v132, v88, v211
	v_fma_f32 v88, v128, v88, v220
	v_fma_f32 v89, v128, v89, v221
	v_mfma_f32_16x16x32_bf16 v[192:195], v[184:187], v[4:7], 0
	v_mfma_f32_16x16x32_bf16 v[208:211], v[184:187], v[20:23], 0
	v_fma_f32 v220, -v132, v89, v196
	v_fma_f32 v221, v132, v88, v212
	v_fma_f32 v88, v128, v88, v220
	v_fma_f32 v89, v128, v89, v221
	v_fma_f32 v220, -v132, v89, v197
	v_fma_f32 v221, v132, v88, v213
	v_fma_f32 v88, v128, v88, v220
	v_fma_f32 v89, v128, v89, v221
	v_fma_f32 v220, -v132, v89, v198
	v_fma_f32 v221, v132, v88, v214
	v_fma_f32 v88, v128, v88, v220
	v_fma_f32 v89, v128, v89, v221
	v_fma_f32 v220, -v132, v89, v199
	v_fma_f32 v221, v132, v88, v215
	v_fma_f32 v88, v128, v88, v220
	v_fma_f32 v89, v128, v89, v221
	v_mfma_f32_16x16x32_bf16 v[196:199], v[184:187], v[8:11], 0
	v_mfma_f32_16x16x32_bf16 v[212:215], v[184:187], v[24:27], 0
	v_fma_f32 v220, -v132, v89, v200
	v_fma_f32 v221, v132, v88, v216
	v_fma_f32 v88, v128, v88, v220
	v_fma_f32 v89, v128, v89, v221
	v_fma_f32 v220, -v132, v89, v201
	v_fma_f32 v221, v132, v88, v217
	v_fma_f32 v88, v128, v88, v220
	v_fma_f32 v89, v128, v89, v221
	v_fma_f32 v220, -v132, v89, v202
	v_fma_f32 v221, v132, v88, v218
	v_fma_f32 v88, v128, v88, v220
	v_fma_f32 v89, v128, v89, v221
	v_fma_f32 v220, -v132, v89, v203
	v_fma_f32 v221, v132, v88, v219
	v_fma_f32 v88, v128, v88, v220
	v_fma_f32 v89, v128, v89, v221
	v_mfma_f32_16x16x32_bf16 v[200:203], v[184:187], v[12:15], 0
	v_mfma_f32_16x16x32_bf16 v[216:219], v[184:187], v[28:31], 0
	s_nop 7
	v_permlane16_swap_b32_e32 v188, v192
	v_permlane16_swap_b32_e32 v189, v193
	v_permlane16_swap_b32_e32 v190, v194
	v_permlane16_swap_b32_e32 v191, v195
	v_permlane16_swap_b32_e32 v196, v200
	v_permlane16_swap_b32_e32 v197, v201
	v_permlane16_swap_b32_e32 v198, v202
	v_permlane16_swap_b32_e32 v199, v203
	v_permlane16_swap_b32_e32 v204, v208
	v_permlane16_swap_b32_e32 v205, v209
	v_permlane16_swap_b32_e32 v206, v210
	v_permlane16_swap_b32_e32 v207, v211
	v_permlane16_swap_b32_e32 v212, v216
	v_permlane16_swap_b32_e32 v213, v217
	v_permlane16_swap_b32_e32 v214, v218
	v_permlane16_swap_b32_e32 v215, v219
	v_permlane32_swap_b32_e32 v188, v196
	v_permlane32_swap_b32_e32 v189, v197
	v_permlane32_swap_b32_e32 v190, v198
	v_permlane32_swap_b32_e32 v191, v199
	v_permlane32_swap_b32_e32 v192, v200
	v_permlane32_swap_b32_e32 v193, v201
	v_permlane32_swap_b32_e32 v194, v202
	v_permlane32_swap_b32_e32 v195, v203
	v_permlane32_swap_b32_e32 v204, v212
	v_permlane32_swap_b32_e32 v205, v213
	v_permlane32_swap_b32_e32 v206, v214
	v_permlane32_swap_b32_e32 v207, v215
	v_permlane32_swap_b32_e32 v208, v216
	v_permlane32_swap_b32_e32 v209, v217
	v_permlane32_swap_b32_e32 v210, v218
	v_permlane32_swap_b32_e32 v211, v219
	s_nop 1
	v_cndmask_b32_e64 v184, v72, 0, s[10:11]
	v_cndmask_b32_e64 v185, v73, 0, s[10:11]
	v_cndmask_b32_e64 v186, v74, 0, s[10:11]
	v_cndmask_b32_e64 v187, v75, 0, s[10:11]
	v_fma_f32 v220, -v132, v89, v188
	v_fma_f32 v221, v132, v88, v204
	v_fma_f32 v88, v128, v88, v220
	v_fma_f32 v89, v128, v89, v221
	v_fma_f32 v220, -v132, v89, v189
	v_fma_f32 v221, v132, v88, v205
	v_fma_f32 v88, v128, v88, v220
	v_fma_f32 v89, v128, v89, v221
	v_fma_f32 v220, -v132, v89, v190
	v_fma_f32 v221, v132, v88, v206
	v_fma_f32 v88, v128, v88, v220
	v_fma_f32 v89, v128, v89, v221
	v_fma_f32 v220, -v132, v89, v191
	v_fma_f32 v221, v132, v88, v207
	v_fma_f32 v88, v128, v88, v220
	v_fma_f32 v89, v128, v89, v221
	v_mfma_f32_16x16x32_bf16 v[188:191], v[184:187], v[0:3], 0
	v_mfma_f32_16x16x32_bf16 v[204:207], v[184:187], v[16:19], 0
	v_fma_f32 v220, -v132, v89, v192
	v_fma_f32 v221, v132, v88, v208
	v_fma_f32 v88, v128, v88, v220
	v_fma_f32 v89, v128, v89, v221
	v_fma_f32 v220, -v132, v89, v193
	v_fma_f32 v221, v132, v88, v209
	v_fma_f32 v88, v128, v88, v220
	v_fma_f32 v89, v128, v89, v221
	v_fma_f32 v220, -v132, v89, v194
	v_fma_f32 v221, v132, v88, v210
	v_fma_f32 v88, v128, v88, v220
	v_fma_f32 v89, v128, v89, v221
	v_fma_f32 v220, -v132, v89, v195
	v_fma_f32 v221, v132, v88, v211
	v_fma_f32 v88, v128, v88, v220
	v_fma_f32 v89, v128, v89, v221
	v_mfma_f32_16x16x32_bf16 v[192:195], v[184:187], v[4:7], 0
	v_mfma_f32_16x16x32_bf16 v[208:211], v[184:187], v[20:23], 0
	v_fma_f32 v220, -v132, v89, v196
	v_fma_f32 v221, v132, v88, v212
	v_fma_f32 v88, v128, v88, v220
	v_fma_f32 v89, v128, v89, v221
	v_fma_f32 v220, -v132, v89, v197
	v_fma_f32 v221, v132, v88, v213
	v_fma_f32 v88, v128, v88, v220
	v_fma_f32 v89, v128, v89, v221
	v_fma_f32 v220, -v132, v89, v198
	v_fma_f32 v221, v132, v88, v214
	v_fma_f32 v88, v128, v88, v220
	v_fma_f32 v89, v128, v89, v221
	v_fma_f32 v220, -v132, v89, v199
	v_fma_f32 v221, v132, v88, v215
	v_fma_f32 v88, v128, v88, v220
	v_fma_f32 v89, v128, v89, v221
	v_mfma_f32_16x16x32_bf16 v[196:199], v[184:187], v[8:11], 0
	v_mfma_f32_16x16x32_bf16 v[212:215], v[184:187], v[24:27], 0
	v_fma_f32 v220, -v132, v89, v200
	v_fma_f32 v221, v132, v88, v216
	v_fma_f32 v88, v128, v88, v220
	v_fma_f32 v89, v128, v89, v221
	v_fma_f32 v220, -v132, v89, v201
	v_fma_f32 v221, v132, v88, v217
	v_fma_f32 v88, v128, v88, v220
	v_fma_f32 v89, v128, v89, v221
	v_fma_f32 v220, -v132, v89, v202
	v_fma_f32 v221, v132, v88, v218
	v_fma_f32 v88, v128, v88, v220
	v_fma_f32 v89, v128, v89, v221
	v_fma_f32 v220, -v132, v89, v203
	v_fma_f32 v221, v132, v88, v219
	v_fma_f32 v88, v128, v88, v220
	v_fma_f32 v89, v128, v89, v221
	v_mfma_f32_16x16x32_bf16 v[200:203], v[184:187], v[12:15], 0
	v_mfma_f32_16x16x32_bf16 v[216:219], v[184:187], v[28:31], 0
	s_nop 7
	v_permlane16_swap_b32_e32 v188, v192
	v_permlane16_swap_b32_e32 v189, v193
	v_permlane16_swap_b32_e32 v190, v194
	v_permlane16_swap_b32_e32 v191, v195
	v_permlane16_swap_b32_e32 v196, v200
	v_permlane16_swap_b32_e32 v197, v201
	v_permlane16_swap_b32_e32 v198, v202
	v_permlane16_swap_b32_e32 v199, v203
	v_permlane16_swap_b32_e32 v204, v208
	v_permlane16_swap_b32_e32 v205, v209
	v_permlane16_swap_b32_e32 v206, v210
	v_permlane16_swap_b32_e32 v207, v211
	v_permlane16_swap_b32_e32 v212, v216
	v_permlane16_swap_b32_e32 v213, v217
	v_permlane16_swap_b32_e32 v214, v218
	v_permlane16_swap_b32_e32 v215, v219
	v_permlane32_swap_b32_e32 v188, v196
	v_permlane32_swap_b32_e32 v189, v197
	v_permlane32_swap_b32_e32 v190, v198
	v_permlane32_swap_b32_e32 v191, v199
	v_permlane32_swap_b32_e32 v192, v200
	v_permlane32_swap_b32_e32 v193, v201
	v_permlane32_swap_b32_e32 v194, v202
	v_permlane32_swap_b32_e32 v195, v203
	v_permlane32_swap_b32_e32 v204, v212
	v_permlane32_swap_b32_e32 v205, v213
	v_permlane32_swap_b32_e32 v206, v214
	v_permlane32_swap_b32_e32 v207, v215
	v_permlane32_swap_b32_e32 v208, v216
	v_permlane32_swap_b32_e32 v209, v217
	v_permlane32_swap_b32_e32 v210, v218
	v_permlane32_swap_b32_e32 v211, v219
	s_nop 1
	v_cndmask_b32_e64 v184, v68, 0, s[10:11]
	v_cndmask_b32_e64 v185, v69, 0, s[10:11]
	v_cndmask_b32_e64 v186, v70, 0, s[10:11]
	v_cndmask_b32_e64 v187, v71, 0, s[10:11]
	v_fma_f32 v220, -v132, v89, v188
	v_fma_f32 v221, v132, v88, v204
	v_fma_f32 v88, v128, v88, v220
	v_fma_f32 v89, v128, v89, v221
	v_fma_f32 v220, -v132, v89, v189
	v_fma_f32 v221, v132, v88, v205
	v_fma_f32 v88, v128, v88, v220
	v_fma_f32 v89, v128, v89, v221
	v_fma_f32 v220, -v132, v89, v190
	v_fma_f32 v221, v132, v88, v206
	v_fma_f32 v88, v128, v88, v220
	v_fma_f32 v89, v128, v89, v221
	v_fma_f32 v220, -v132, v89, v191
	v_fma_f32 v221, v132, v88, v207
	v_fma_f32 v88, v128, v88, v220
	v_fma_f32 v89, v128, v89, v221
	v_mfma_f32_16x16x32_bf16 v[188:191], v[184:187], v[0:3], 0
	v_mfma_f32_16x16x32_bf16 v[204:207], v[184:187], v[16:19], 0
	v_fma_f32 v220, -v132, v89, v192
	v_fma_f32 v221, v132, v88, v208
	v_fma_f32 v88, v128, v88, v220
	v_fma_f32 v89, v128, v89, v221
	v_fma_f32 v220, -v132, v89, v193
	v_fma_f32 v221, v132, v88, v209
	v_fma_f32 v88, v128, v88, v220
	v_fma_f32 v89, v128, v89, v221
	v_fma_f32 v220, -v132, v89, v194
	v_fma_f32 v221, v132, v88, v210
	v_fma_f32 v88, v128, v88, v220
	v_fma_f32 v89, v128, v89, v221
	v_fma_f32 v220, -v132, v89, v195
	v_fma_f32 v221, v132, v88, v211
	v_fma_f32 v88, v128, v88, v220
	v_fma_f32 v89, v128, v89, v221
	v_mfma_f32_16x16x32_bf16 v[192:195], v[184:187], v[4:7], 0
	v_mfma_f32_16x16x32_bf16 v[208:211], v[184:187], v[20:23], 0
	v_fma_f32 v220, -v132, v89, v196
	v_fma_f32 v221, v132, v88, v212
	v_fma_f32 v88, v128, v88, v220
	v_fma_f32 v89, v128, v89, v221
	v_fma_f32 v220, -v132, v89, v197
	v_fma_f32 v221, v132, v88, v213
	v_fma_f32 v88, v128, v88, v220
	v_fma_f32 v89, v128, v89, v221
	v_fma_f32 v220, -v132, v89, v198
	v_fma_f32 v221, v132, v88, v214
	v_fma_f32 v88, v128, v88, v220
	v_fma_f32 v89, v128, v89, v221
	v_fma_f32 v220, -v132, v89, v199
	v_fma_f32 v221, v132, v88, v215
	v_fma_f32 v88, v128, v88, v220
	v_fma_f32 v89, v128, v89, v221
	v_mfma_f32_16x16x32_bf16 v[196:199], v[184:187], v[8:11], 0
	v_mfma_f32_16x16x32_bf16 v[212:215], v[184:187], v[24:27], 0
	v_fma_f32 v220, -v132, v89, v200
	v_fma_f32 v221, v132, v88, v216
	v_fma_f32 v88, v128, v88, v220
	v_fma_f32 v89, v128, v89, v221
	v_fma_f32 v220, -v132, v89, v201
	v_fma_f32 v221, v132, v88, v217
	v_fma_f32 v88, v128, v88, v220
	v_fma_f32 v89, v128, v89, v221
	v_fma_f32 v220, -v132, v89, v202
	v_fma_f32 v221, v132, v88, v218
	v_fma_f32 v88, v128, v88, v220
	v_fma_f32 v89, v128, v89, v221
	v_fma_f32 v220, -v132, v89, v203
	v_fma_f32 v221, v132, v88, v219
	v_fma_f32 v88, v128, v88, v220
	v_fma_f32 v89, v128, v89, v221
	v_mfma_f32_16x16x32_bf16 v[200:203], v[184:187], v[12:15], 0
	v_mfma_f32_16x16x32_bf16 v[216:219], v[184:187], v[28:31], 0
	s_nop 7
	v_permlane16_swap_b32_e32 v188, v192
	v_permlane16_swap_b32_e32 v189, v193
	v_permlane16_swap_b32_e32 v190, v194
	v_permlane16_swap_b32_e32 v191, v195
	v_permlane16_swap_b32_e32 v196, v200
	v_permlane16_swap_b32_e32 v197, v201
	v_permlane16_swap_b32_e32 v198, v202
	v_permlane16_swap_b32_e32 v199, v203
	v_permlane16_swap_b32_e32 v204, v208
	v_permlane16_swap_b32_e32 v205, v209
	v_permlane16_swap_b32_e32 v206, v210
	v_permlane16_swap_b32_e32 v207, v211
	v_permlane16_swap_b32_e32 v212, v216
	v_permlane16_swap_b32_e32 v213, v217
	v_permlane16_swap_b32_e32 v214, v218
	v_permlane16_swap_b32_e32 v215, v219
	v_permlane32_swap_b32_e32 v188, v196
	v_permlane32_swap_b32_e32 v189, v197
	v_permlane32_swap_b32_e32 v190, v198
	v_permlane32_swap_b32_e32 v191, v199
	v_permlane32_swap_b32_e32 v192, v200
	v_permlane32_swap_b32_e32 v193, v201
	v_permlane32_swap_b32_e32 v194, v202
	v_permlane32_swap_b32_e32 v195, v203
	v_permlane32_swap_b32_e32 v204, v212
	v_permlane32_swap_b32_e32 v205, v213
	v_permlane32_swap_b32_e32 v206, v214
	v_permlane32_swap_b32_e32 v207, v215
	v_permlane32_swap_b32_e32 v208, v216
	v_permlane32_swap_b32_e32 v209, v217
	v_permlane32_swap_b32_e32 v210, v218
	v_permlane32_swap_b32_e32 v211, v219
	s_nop 1
	v_fma_f32 v220, -v132, v89, v188
	v_fma_f32 v221, v132, v88, v204
	v_fma_f32 v88, v128, v88, v220
	v_fma_f32 v89, v128, v89, v221
	v_fma_f32 v220, -v132, v89, v189
	v_fma_f32 v221, v132, v88, v205
	v_fma_f32 v88, v128, v88, v220
	v_fma_f32 v89, v128, v89, v221
	v_fma_f32 v220, -v132, v89, v190
	v_fma_f32 v221, v132, v88, v206
	v_fma_f32 v88, v128, v88, v220
	v_fma_f32 v89, v128, v89, v221
	v_fma_f32 v220, -v132, v89, v191
	v_fma_f32 v221, v132, v88, v207
	v_fma_f32 v88, v128, v88, v220
	v_fma_f32 v89, v128, v89, v221
	v_fma_f32 v220, -v132, v89, v192
	v_fma_f32 v221, v132, v88, v208
	v_fma_f32 v88, v128, v88, v220
	v_fma_f32 v89, v128, v89, v221
	v_fma_f32 v220, -v132, v89, v193
	v_fma_f32 v221, v132, v88, v209
	v_fma_f32 v88, v128, v88, v220
	v_fma_f32 v89, v128, v89, v221
	v_fma_f32 v220, -v132, v89, v194
	v_fma_f32 v221, v132, v88, v210
	v_fma_f32 v88, v128, v88, v220
	v_fma_f32 v89, v128, v89, v221
	v_fma_f32 v220, -v132, v89, v195
	v_fma_f32 v221, v132, v88, v211
	v_fma_f32 v88, v128, v88, v220
	v_fma_f32 v89, v128, v89, v221
	v_fma_f32 v220, -v132, v89, v196
	v_fma_f32 v221, v132, v88, v212
	v_fma_f32 v88, v128, v88, v220
	v_fma_f32 v89, v128, v89, v221
	v_fma_f32 v220, -v132, v89, v197
	v_fma_f32 v221, v132, v88, v213
	v_fma_f32 v88, v128, v88, v220
	v_fma_f32 v89, v128, v89, v221
	v_fma_f32 v220, -v132, v89, v198
	v_fma_f32 v221, v132, v88, v214
	v_fma_f32 v88, v128, v88, v220
	v_fma_f32 v89, v128, v89, v221
	v_fma_f32 v220, -v132, v89, v199
	v_fma_f32 v221, v132, v88, v215
	v_fma_f32 v88, v128, v88, v220
	v_fma_f32 v89, v128, v89, v221
	v_fma_f32 v220, -v132, v89, v200
	v_fma_f32 v221, v132, v88, v216
	v_fma_f32 v88, v128, v88, v220
	v_fma_f32 v89, v128, v89, v221
	v_fma_f32 v220, -v132, v89, v201
	v_fma_f32 v221, v132, v88, v217
	v_fma_f32 v88, v128, v88, v220
	v_fma_f32 v89, v128, v89, v221
	v_fma_f32 v220, -v132, v89, v202
	v_fma_f32 v221, v132, v88, v218
	v_fma_f32 v88, v128, v88, v220
	v_fma_f32 v89, v128, v89, v221
	v_fma_f32 v220, -v132, v89, v203
	v_fma_f32 v221, v132, v88, v219
	v_fma_f32 v88, v128, v88, v220
	v_fma_f32 v89, v128, v89, v221
	s_add_i32 s34, s34, 1
	s_add_u32 s30, s30, 0x40000
	s_addc_u32 s31, s31, 0
	s_cmp_eq_u32 s30, 0x200000
	s_cbranch_scc1 .LBB0_850
	s_waitcnt vmcnt(0)
	v_mov_b64_e32 v[70:71], v[66:67]
	v_mov_b64_e32 v[74:75], v[62:63]
	v_mov_b64_e32 v[78:79], v[58:59]
	v_mov_b64_e32 v[82:83], v[54:55]
	v_mov_b64_e32 v[68:69], v[64:65]
	v_mov_b64_e32 v[72:73], v[60:61]
	v_mov_b64_e32 v[76:77], v[56:57]
	v_mov_b64_e32 v[80:81], v[52:53]
	s_cmp_gt_u32 s34, 6
	s_cbranch_scc0 .LBB0_847
	s_branch .LBB0_848
